# v42: v41 + prologue XB/sum-of-squares loop straight-lined for its 8 row pairs per wave: next pair's loads in flight during conversion and reduction, both row reductions side by side, global stores
# baseline (speedup 1.0000x reference)
.LBB0_366:
	s_or_b64 exec, exec, s[0:1]
	s_cmpk_gt_i32 s5, 0x3fff
	s_cbranch_scc1 .LBB0_374
	s_lshl_b32 s0, s5, 1
	v_cmp_lt_i32_e32 vcc, v205, v204
	s_ashr_i32 s1, s0, 31
	s_lshl_b64 s[2:3], s[0:1], 6
	v_cndmask_b32_e32 v0, v202, v205, vcc
	v_cmp_lt_i32_e32 vcc, v206, v204
	v_lshlrev_b32_e32 v26, 2, v0
	v_lshlrev_b32_e32 v192, 2, v214
	v_cndmask_b32_e32 v0, v202, v206, vcc
	v_cmp_lt_i32_e32 vcc, v207, v204
	v_lshlrev_b32_e32 v27, 2, v0
	v_lshl_add_u64 v[16:17], s[2:3], 0, v[192:193]
	v_cndmask_b32_e32 v0, v202, v207, vcc
	v_cmp_lt_i32_e32 vcc, v208, v204
	s_lshl_b64 s[2:3], s[0:1], 11
	v_lshlrev_b32_e32 v28, 2, v0
	v_cndmask_b32_e32 v0, v202, v208, vcc
	v_cmp_lt_i32_e32 vcc, v209, v204
	v_lshl_or_b32 v18, v214, 3, s2
	v_mov_b32_e32 v19, s3
	s_lshl_b64 s[2:3], s[0:1], 12
	v_readlane_b32 s1, v245, 3
	v_lshlrev_b32_e32 v29, 2, v0
	v_cndmask_b32_e32 v0, v202, v209, vcc
	v_cmp_lt_i32_e32 vcc, v210, v204
	s_add_u32 s2, s1, s2
	v_readlane_b32 s1, v245, 4
	v_lshlrev_b32_e32 v30, 2, v0
	v_cndmask_b32_e32 v0, v202, v210, vcc
	v_lshlrev_b32_e32 v192, 4, v214
	s_addc_u32 s3, s1, s3
	v_lshlrev_b32_e32 v31, 2, v0
	v_cmp_gt_u32_e64 s[36:37], 16, v214
	v_cmp_eq_u32_e64 s[38:39], 0, v214
	v_lshl_add_u64 v[20:21], s[2:3], 0, v[192:193]
	v_readlane_b32 s2, v245, 15
	s_cmp_eq_u32 s2, 0x1000
	s_cbranch_scc1 .Lxb_fast
	s_branch .LBB0_369

.Lxb_fast:
	v_readlane_b32 s8, v246, 63
	v_readlane_b32 s9, v245, 0
	v_readlane_b32 s10, v245, 1
	v_readlane_b32 s11, v245, 2
	v_readlane_b32 s12, v245, 17
	v_readlane_b32 s13, v245, 18
	s_waitcnt lgkmcnt(0)
	global_load_dwordx4 v[22:25], v[20:21], off offset:-4096 nt
	global_load_dwordx4 v[32:35], v[20:21], off offset:-3072 nt
	global_load_dwordx4 v[36:39], v[20:21], off offset:-2048 nt
	global_load_dwordx4 v[40:43], v[20:21], off offset:-1024 nt
	global_load_dwordx4 v[12:15], v[20:21], off nt
	global_load_dwordx4 v[8:11], v[20:21], off offset:1024 nt
	global_load_dwordx4 v[4:7], v[20:21], off offset:2048 nt
	global_load_dwordx4 v[0:3], v[20:21], off offset:3072 nt
	s_mov_b64 vcc, 0x6000000
	v_lshl_add_u64 v[82:83], s[6:7], 0, v[18:19]
	v_lshl_add_u64 v[82:83], v[82:83], 0, vcc
	s_mov_b64 vcc, 0x1e000000
	v_lshl_add_u64 v[84:85], s[6:7], 0, v[16:17]
	v_lshl_add_u64 v[84:85], v[84:85], 0, vcc
	v_lshl_add_u64 v[20:21], v[20:21], 0, s[12:13]
	global_load_dwordx4 v[50:53], v[20:21], off offset:-4096 nt
	global_load_dwordx4 v[54:57], v[20:21], off offset:-3072 nt
	global_load_dwordx4 v[58:61], v[20:21], off offset:-2048 nt
	global_load_dwordx4 v[62:65], v[20:21], off offset:-1024 nt
	global_load_dwordx4 v[66:69], v[20:21], off nt
	global_load_dwordx4 v[70:73], v[20:21], off offset:1024 nt
	global_load_dwordx4 v[74:77], v[20:21], off offset:2048 nt
	global_load_dwordx4 v[78:81], v[20:21], off offset:3072 nt
	v_lshl_add_u64 v[16:17], v[16:17], 0, s[8:9]
	v_lshl_add_u64 v[18:19], v[18:19], 0, s[10:11]
	s_waitcnt vmcnt(8)
	v_mul_f32_e32 v44, v23, v23
	v_mul_f32_e32 v45, v25, v25
	v_fmac_f32_e32 v44, v22, v22
	v_fmac_f32_e32 v45, v24, v24
	v_add_f32_e32 v46, v44, v45
	v_cvt_pk_bf16_f32 v88, v22, v23
	v_cvt_pk_bf16_f32 v89, v24, v25
	global_store_dwordx2 v[82:83], v[88:89], off
	v_mul_f32_e32 v44, v33, v33
	v_mul_f32_e32 v45, v35, v35
	v_fmac_f32_e32 v44, v32, v32
	v_fmac_f32_e32 v45, v34, v34
	v_add_f32_e32 v44, v44, v45
	v_add_f32_e32 v46, v46, v44
	v_cvt_pk_bf16_f32 v90, v32, v33
	v_cvt_pk_bf16_f32 v91, v34, v35
	global_store_dwordx2 v[82:83], v[90:91], off offset:512
	v_mul_f32_e32 v44, v37, v37
	v_mul_f32_e32 v45, v39, v39
	v_fmac_f32_e32 v44, v36, v36
	v_fmac_f32_e32 v45, v38, v38
	v_add_f32_e32 v44, v44, v45
	v_add_f32_e32 v46, v46, v44
	v_cvt_pk_bf16_f32 v88, v36, v37
	v_cvt_pk_bf16_f32 v89, v38, v39
	global_store_dwordx2 v[82:83], v[88:89], off offset:1024
	v_mul_f32_e32 v44, v41, v41
	v_mul_f32_e32 v45, v43, v43
	v_fmac_f32_e32 v44, v40, v40
	v_fmac_f32_e32 v45, v42, v42
	v_add_f32_e32 v44, v44, v45
	v_add_f32_e32 v46, v46, v44
	v_cvt_pk_bf16_f32 v90, v40, v41
	v_cvt_pk_bf16_f32 v91, v42, v43
	global_store_dwordx2 v[82:83], v[90:91], off offset:1536
	v_mul_f32_e32 v44, v13, v13
	v_mul_f32_e32 v45, v15, v15
	v_fmac_f32_e32 v44, v12, v12
	v_fmac_f32_e32 v45, v14, v14
	v_add_f32_e32 v47, v44, v45
	v_cvt_pk_bf16_f32 v88, v12, v13
	v_cvt_pk_bf16_f32 v89, v14, v15
	global_store_dwordx2 v[82:83], v[88:89], off offset:2048
	v_mul_f32_e32 v44, v9, v9
	v_mul_f32_e32 v45, v11, v11
	v_fmac_f32_e32 v44, v8, v8
	v_fmac_f32_e32 v45, v10, v10
	v_add_f32_e32 v44, v44, v45
	v_add_f32_e32 v47, v47, v44
	v_cvt_pk_bf16_f32 v90, v8, v9
	v_cvt_pk_bf16_f32 v91, v10, v11
	global_store_dwordx2 v[82:83], v[90:91], off offset:2560
	v_mul_f32_e32 v44, v5, v5
	v_mul_f32_e32 v45, v7, v7
	v_fmac_f32_e32 v44, v4, v4
	v_fmac_f32_e32 v45, v6, v6
	v_add_f32_e32 v44, v44, v45
	v_add_f32_e32 v47, v47, v44
	v_cvt_pk_bf16_f32 v88, v4, v5
	v_cvt_pk_bf16_f32 v89, v6, v7
	global_store_dwordx2 v[82:83], v[88:89], off offset:3072
	v_mul_f32_e32 v44, v1, v1
	v_mul_f32_e32 v45, v3, v3
	v_fmac_f32_e32 v44, v0, v0
	v_fmac_f32_e32 v45, v2, v2
	v_add_f32_e32 v44, v44, v45
	v_add_f32_e32 v47, v47, v44
	v_cvt_pk_bf16_f32 v90, v0, v1
	v_cvt_pk_bf16_f32 v91, v2, v3
	global_store_dwordx2 v[82:83], v[90:91], off offset:3584
	ds_bpermute_b32 v86, v26, v46
	ds_bpermute_b32 v87, v26, v47
	s_waitcnt lgkmcnt(0)
	v_add_f32_e32 v46, v46, v86
	v_add_f32_e32 v47, v47, v87
	ds_bpermute_b32 v86, v27, v46
	ds_bpermute_b32 v87, v27, v47
	s_waitcnt lgkmcnt(0)
	v_add_f32_e32 v46, v46, v86
	v_add_f32_e32 v47, v47, v87
	ds_bpermute_b32 v86, v28, v46
	ds_bpermute_b32 v87, v28, v47
	s_waitcnt lgkmcnt(0)
	v_add_f32_e32 v46, v46, v86
	v_add_f32_e32 v47, v47, v87
	ds_bpermute_b32 v86, v29, v46
	ds_bpermute_b32 v87, v29, v47
	s_waitcnt lgkmcnt(0)
	v_add_f32_e32 v46, v46, v86
	v_add_f32_e32 v47, v47, v87
	ds_bpermute_b32 v86, v30, v46
	ds_bpermute_b32 v87, v30, v47
	s_waitcnt lgkmcnt(0)
	v_add_f32_e32 v46, v46, v86
	v_add_f32_e32 v47, v47, v87
	ds_bpermute_b32 v86, v31, v46
	ds_bpermute_b32 v87, v31, v47
	s_waitcnt lgkmcnt(0)
	v_add_f32_e32 v46, v46, v86
	v_add_f32_e32 v47, v47, v87
	s_and_saveexec_b64 s[2:3], s[36:37]
	v_cndmask_b32_e64 v86, 0, v46, s[38:39]
	v_cndmask_b32_e64 v87, 0, v47, s[38:39]
	global_store_dword v[84:85], v86, off
	global_store_dword v[84:85], v87, off offset:64
	s_or_b64 exec, exec, s[2:3]
	s_mov_b64 vcc, 0x6000000
	v_lshl_add_u64 v[82:83], s[6:7], 0, v[18:19]
	v_lshl_add_u64 v[82:83], v[82:83], 0, vcc
	s_mov_b64 vcc, 0x1e000000
	v_lshl_add_u64 v[84:85], s[6:7], 0, v[16:17]
	v_lshl_add_u64 v[84:85], v[84:85], 0, vcc
	v_lshl_add_u64 v[20:21], v[20:21], 0, s[12:13]
	global_load_dwordx4 v[22:25], v[20:21], off offset:-4096 nt
	global_load_dwordx4 v[32:35], v[20:21], off offset:-3072 nt
	global_load_dwordx4 v[36:39], v[20:21], off offset:-2048 nt
	global_load_dwordx4 v[40:43], v[20:21], off offset:-1024 nt
	global_load_dwordx4 v[12:15], v[20:21], off nt
	global_load_dwordx4 v[8:11], v[20:21], off offset:1024 nt
	global_load_dwordx4 v[4:7], v[20:21], off offset:2048 nt
	global_load_dwordx4 v[0:3], v[20:21], off offset:3072 nt
	v_lshl_add_u64 v[16:17], v[16:17], 0, s[8:9]
	v_lshl_add_u64 v[18:19], v[18:19], 0, s[10:11]
	s_waitcnt vmcnt(16)
	v_mul_f32_e32 v44, v51, v51
	v_mul_f32_e32 v45, v53, v53
	v_fmac_f32_e32 v44, v50, v50
	v_fmac_f32_e32 v45, v52, v52
	v_add_f32_e32 v46, v44, v45
	v_cvt_pk_bf16_f32 v88, v50, v51
	v_cvt_pk_bf16_f32 v89, v52, v53
	global_store_dwordx2 v[82:83], v[88:89], off
	v_mul_f32_e32 v44, v55, v55
	v_mul_f32_e32 v45, v57, v57
	v_fmac_f32_e32 v44, v54, v54
	v_fmac_f32_e32 v45, v56, v56
	v_add_f32_e32 v44, v44, v45
	v_add_f32_e32 v46, v46, v44
	v_cvt_pk_bf16_f32 v90, v54, v55
	v_cvt_pk_bf16_f32 v91, v56, v57
	global_store_dwordx2 v[82:83], v[90:91], off offset:512
	v_mul_f32_e32 v44, v59, v59
	v_mul_f32_e32 v45, v61, v61
	v_fmac_f32_e32 v44, v58, v58
	v_fmac_f32_e32 v45, v60, v60
	v_add_f32_e32 v44, v44, v45
	v_add_f32_e32 v46, v46, v44
	v_cvt_pk_bf16_f32 v88, v58, v59
	v_cvt_pk_bf16_f32 v89, v60, v61
	global_store_dwordx2 v[82:83], v[88:89], off offset:1024
	v_mul_f32_e32 v44, v63, v63
	v_mul_f32_e32 v45, v65, v65
	v_fmac_f32_e32 v44, v62, v62
	v_fmac_f32_e32 v45, v64, v64
	v_add_f32_e32 v44, v44, v45
	v_add_f32_e32 v46, v46, v44
	v_cvt_pk_bf16_f32 v90, v62, v63
	v_cvt_pk_bf16_f32 v91, v64, v65
	global_store_dwordx2 v[82:83], v[90:91], off offset:1536
	v_mul_f32_e32 v44, v67, v67
	v_mul_f32_e32 v45, v69, v69
	v_fmac_f32_e32 v44, v66, v66
	v_fmac_f32_e32 v45, v68, v68
	v_add_f32_e32 v47, v44, v45
	v_cvt_pk_bf16_f32 v88, v66, v67
	v_cvt_pk_bf16_f32 v89, v68, v69
	global_store_dwordx2 v[82:83], v[88:89], off offset:2048
	v_mul_f32_e32 v44, v71, v71
	v_mul_f32_e32 v45, v73, v73
	v_fmac_f32_e32 v44, v70, v70
	v_fmac_f32_e32 v45, v72, v72
	v_add_f32_e32 v44, v44, v45
	v_add_f32_e32 v47, v47, v44
	v_cvt_pk_bf16_f32 v90, v70, v71
	v_cvt_pk_bf16_f32 v91, v72, v73
	global_store_dwordx2 v[82:83], v[90:91], off offset:2560
	v_mul_f32_e32 v44, v75, v75
	v_mul_f32_e32 v45, v77, v77
	v_fmac_f32_e32 v44, v74, v74
	v_fmac_f32_e32 v45, v76, v76
	v_add_f32_e32 v44, v44, v45
	v_add_f32_e32 v47, v47, v44
	v_cvt_pk_bf16_f32 v88, v74, v75
	v_cvt_pk_bf16_f32 v89, v76, v77
	global_store_dwordx2 v[82:83], v[88:89], off offset:3072
	v_mul_f32_e32 v44, v79, v79
	v_mul_f32_e32 v45, v81, v81
	v_fmac_f32_e32 v44, v78, v78
	v_fmac_f32_e32 v45, v80, v80
	v_add_f32_e32 v44, v44, v45
	v_add_f32_e32 v47, v47, v44
	v_cvt_pk_bf16_f32 v90, v78, v79
	v_cvt_pk_bf16_f32 v91, v80, v81
	global_store_dwordx2 v[82:83], v[90:91], off offset:3584
	ds_bpermute_b32 v86, v26, v46
	ds_bpermute_b32 v87, v26, v47
	s_waitcnt lgkmcnt(0)
	v_add_f32_e32 v46, v46, v86
	v_add_f32_e32 v47, v47, v87
	ds_bpermute_b32 v86, v27, v46
	ds_bpermute_b32 v87, v27, v47
	s_waitcnt lgkmcnt(0)
	v_add_f32_e32 v46, v46, v86
	v_add_f32_e32 v47, v47, v87
	ds_bpermute_b32 v86, v28, v46
	ds_bpermute_b32 v87, v28, v47
	s_waitcnt lgkmcnt(0)
	v_add_f32_e32 v46, v46, v86
	v_add_f32_e32 v47, v47, v87
	ds_bpermute_b32 v86, v29, v46
	ds_bpermute_b32 v87, v29, v47
	s_waitcnt lgkmcnt(0)
	v_add_f32_e32 v46, v46, v86
	v_add_f32_e32 v47, v47, v87
	ds_bpermute_b32 v86, v30, v46
	ds_bpermute_b32 v87, v30, v47
	s_waitcnt lgkmcnt(0)
	v_add_f32_e32 v46, v46, v86
	v_add_f32_e32 v47, v47, v87
	ds_bpermute_b32 v86, v31, v46
	ds_bpermute_b32 v87, v31, v47
	s_waitcnt lgkmcnt(0)
	v_add_f32_e32 v46, v46, v86
	v_add_f32_e32 v47, v47, v87
	s_and_saveexec_b64 s[2:3], s[36:37]
	v_cndmask_b32_e64 v86, 0, v46, s[38:39]
	v_cndmask_b32_e64 v87, 0, v47, s[38:39]
	global_store_dword v[84:85], v86, off
	global_store_dword v[84:85], v87, off offset:64
	s_or_b64 exec, exec, s[2:3]
	s_mov_b64 vcc, 0x6000000
	v_lshl_add_u64 v[82:83], s[6:7], 0, v[18:19]
	v_lshl_add_u64 v[82:83], v[82:83], 0, vcc
	s_mov_b64 vcc, 0x1e000000
	v_lshl_add_u64 v[84:85], s[6:7], 0, v[16:17]
	v_lshl_add_u64 v[84:85], v[84:85], 0, vcc
	v_lshl_add_u64 v[20:21], v[20:21], 0, s[12:13]
	global_load_dwordx4 v[50:53], v[20:21], off offset:-4096 nt
	global_load_dwordx4 v[54:57], v[20:21], off offset:-3072 nt
	global_load_dwordx4 v[58:61], v[20:21], off offset:-2048 nt
	global_load_dwordx4 v[62:65], v[20:21], off offset:-1024 nt
	global_load_dwordx4 v[66:69], v[20:21], off nt
	global_load_dwordx4 v[70:73], v[20:21], off offset:1024 nt
	global_load_dwordx4 v[74:77], v[20:21], off offset:2048 nt
	global_load_dwordx4 v[78:81], v[20:21], off offset:3072 nt
	v_lshl_add_u64 v[16:17], v[16:17], 0, s[8:9]
	v_lshl_add_u64 v[18:19], v[18:19], 0, s[10:11]
	s_waitcnt vmcnt(16)
	v_mul_f32_e32 v44, v23, v23
	v_mul_f32_e32 v45, v25, v25
	v_fmac_f32_e32 v44, v22, v22
	v_fmac_f32_e32 v45, v24, v24
	v_add_f32_e32 v46, v44, v45
	v_cvt_pk_bf16_f32 v88, v22, v23
	v_cvt_pk_bf16_f32 v89, v24, v25
	global_store_dwordx2 v[82:83], v[88:89], off
	v_mul_f32_e32 v44, v33, v33
	v_mul_f32_e32 v45, v35, v35
	v_fmac_f32_e32 v44, v32, v32
	v_fmac_f32_e32 v45, v34, v34
	v_add_f32_e32 v44, v44, v45
	v_add_f32_e32 v46, v46, v44
	v_cvt_pk_bf16_f32 v90, v32, v33
	v_cvt_pk_bf16_f32 v91, v34, v35
	global_store_dwordx2 v[82:83], v[90:91], off offset:512
	v_mul_f32_e32 v44, v37, v37
	v_mul_f32_e32 v45, v39, v39
	v_fmac_f32_e32 v44, v36, v36
	v_fmac_f32_e32 v45, v38, v38
	v_add_f32_e32 v44, v44, v45
	v_add_f32_e32 v46, v46, v44
	v_cvt_pk_bf16_f32 v88, v36, v37
	v_cvt_pk_bf16_f32 v89, v38, v39
	global_store_dwordx2 v[82:83], v[88:89], off offset:1024
	v_mul_f32_e32 v44, v41, v41
	v_mul_f32_e32 v45, v43, v43
	v_fmac_f32_e32 v44, v40, v40
	v_fmac_f32_e32 v45, v42, v42
	v_add_f32_e32 v44, v44, v45
	v_add_f32_e32 v46, v46, v44
	v_cvt_pk_bf16_f32 v90, v40, v41
	v_cvt_pk_bf16_f32 v91, v42, v43
	global_store_dwordx2 v[82:83], v[90:91], off offset:1536
	v_mul_f32_e32 v44, v13, v13
	v_mul_f32_e32 v45, v15, v15
	v_fmac_f32_e32 v44, v12, v12
	v_fmac_f32_e32 v45, v14, v14
	v_add_f32_e32 v47, v44, v45
	v_cvt_pk_bf16_f32 v88, v12, v13
	v_cvt_pk_bf16_f32 v89, v14, v15
	global_store_dwordx2 v[82:83], v[88:89], off offset:2048
	v_mul_f32_e32 v44, v9, v9
	v_mul_f32_e32 v45, v11, v11
	v_fmac_f32_e32 v44, v8, v8
	v_fmac_f32_e32 v45, v10, v10
	v_add_f32_e32 v44, v44, v45
	v_add_f32_e32 v47, v47, v44
	v_cvt_pk_bf16_f32 v90, v8, v9
	v_cvt_pk_bf16_f32 v91, v10, v11
	global_store_dwordx2 v[82:83], v[90:91], off offset:2560
	v_mul_f32_e32 v44, v5, v5
	v_mul_f32_e32 v45, v7, v7
	v_fmac_f32_e32 v44, v4, v4
	v_fmac_f32_e32 v45, v6, v6
	v_add_f32_e32 v44, v44, v45
	v_add_f32_e32 v47, v47, v44
	v_cvt_pk_bf16_f32 v88, v4, v5
	v_cvt_pk_bf16_f32 v89, v6, v7
	global_store_dwordx2 v[82:83], v[88:89], off offset:3072
	v_mul_f32_e32 v44, v1, v1
	v_mul_f32_e32 v45, v3, v3
	v_fmac_f32_e32 v44, v0, v0
	v_fmac_f32_e32 v45, v2, v2
	v_add_f32_e32 v44, v44, v45
	v_add_f32_e32 v47, v47, v44
	v_cvt_pk_bf16_f32 v90, v0, v1
	v_cvt_pk_bf16_f32 v91, v2, v3
	global_store_dwordx2 v[82:83], v[90:91], off offset:3584
	ds_bpermute_b32 v86, v26, v46
	ds_bpermute_b32 v87, v26, v47
	s_waitcnt lgkmcnt(0)
	v_add_f32_e32 v46, v46, v86
	v_add_f32_e32 v47, v47, v87
	ds_bpermute_b32 v86, v27, v46
	ds_bpermute_b32 v87, v27, v47
	s_waitcnt lgkmcnt(0)
	v_add_f32_e32 v46, v46, v86
	v_add_f32_e32 v47, v47, v87
	ds_bpermute_b32 v86, v28, v46
	ds_bpermute_b32 v87, v28, v47
	s_waitcnt lgkmcnt(0)
	v_add_f32_e32 v46, v46, v86
	v_add_f32_e32 v47, v47, v87
	ds_bpermute_b32 v86, v29, v46
	ds_bpermute_b32 v87, v29, v47
	s_waitcnt lgkmcnt(0)
	v_add_f32_e32 v46, v46, v86
	v_add_f32_e32 v47, v47, v87
	ds_bpermute_b32 v86, v30, v46
	ds_bpermute_b32 v87, v30, v47
	s_waitcnt lgkmcnt(0)
	v_add_f32_e32 v46, v46, v86
	v_add_f32_e32 v47, v47, v87
	ds_bpermute_b32 v86, v31, v46
	ds_bpermute_b32 v87, v31, v47
	s_waitcnt lgkmcnt(0)
	v_add_f32_e32 v46, v46, v86
	v_add_f32_e32 v47, v47, v87
	s_and_saveexec_b64 s[2:3], s[36:37]
	v_cndmask_b32_e64 v86, 0, v46, s[38:39]
	v_cndmask_b32_e64 v87, 0, v47, s[38:39]
	global_store_dword v[84:85], v86, off
	global_store_dword v[84:85], v87, off offset:64
	s_or_b64 exec, exec, s[2:3]
	s_mov_b64 vcc, 0x6000000
	v_lshl_add_u64 v[82:83], s[6:7], 0, v[18:19]
	v_lshl_add_u64 v[82:83], v[82:83], 0, vcc
	s_mov_b64 vcc, 0x1e000000
	v_lshl_add_u64 v[84:85], s[6:7], 0, v[16:17]
	v_lshl_add_u64 v[84:85], v[84:85], 0, vcc
	v_lshl_add_u64 v[20:21], v[20:21], 0, s[12:13]
	global_load_dwordx4 v[22:25], v[20:21], off offset:-4096 nt
	global_load_dwordx4 v[32:35], v[20:21], off offset:-3072 nt
	global_load_dwordx4 v[36:39], v[20:21], off offset:-2048 nt
	global_load_dwordx4 v[40:43], v[20:21], off offset:-1024 nt
	global_load_dwordx4 v[12:15], v[20:21], off nt
	global_load_dwordx4 v[8:11], v[20:21], off offset:1024 nt
	global_load_dwordx4 v[4:7], v[20:21], off offset:2048 nt
	global_load_dwordx4 v[0:3], v[20:21], off offset:3072 nt
	v_lshl_add_u64 v[16:17], v[16:17], 0, s[8:9]
	v_lshl_add_u64 v[18:19], v[18:19], 0, s[10:11]
	s_waitcnt vmcnt(16)
	v_mul_f32_e32 v44, v51, v51
	v_mul_f32_e32 v45, v53, v53
	v_fmac_f32_e32 v44, v50, v50
	v_fmac_f32_e32 v45, v52, v52
	v_add_f32_e32 v46, v44, v45
	v_cvt_pk_bf16_f32 v88, v50, v51
	v_cvt_pk_bf16_f32 v89, v52, v53
	global_store_dwordx2 v[82:83], v[88:89], off
	v_mul_f32_e32 v44, v55, v55
	v_mul_f32_e32 v45, v57, v57
	v_fmac_f32_e32 v44, v54, v54
	v_fmac_f32_e32 v45, v56, v56
	v_add_f32_e32 v44, v44, v45
	v_add_f32_e32 v46, v46, v44
	v_cvt_pk_bf16_f32 v90, v54, v55
	v_cvt_pk_bf16_f32 v91, v56, v57
	global_store_dwordx2 v[82:83], v[90:91], off offset:512
	v_mul_f32_e32 v44, v59, v59
	v_mul_f32_e32 v45, v61, v61
	v_fmac_f32_e32 v44, v58, v58
	v_fmac_f32_e32 v45, v60, v60
	v_add_f32_e32 v44, v44, v45
	v_add_f32_e32 v46, v46, v44
	v_cvt_pk_bf16_f32 v88, v58, v59
	v_cvt_pk_bf16_f32 v89, v60, v61
	global_store_dwordx2 v[82:83], v[88:89], off offset:1024
	v_mul_f32_e32 v44, v63, v63
	v_mul_f32_e32 v45, v65, v65
	v_fmac_f32_e32 v44, v62, v62
	v_fmac_f32_e32 v45, v64, v64
	v_add_f32_e32 v44, v44, v45
	v_add_f32_e32 v46, v46, v44
	v_cvt_pk_bf16_f32 v90, v62, v63
	v_cvt_pk_bf16_f32 v91, v64, v65
	global_store_dwordx2 v[82:83], v[90:91], off offset:1536
	v_mul_f32_e32 v44, v67, v67
	v_mul_f32_e32 v45, v69, v69
	v_fmac_f32_e32 v44, v66, v66
	v_fmac_f32_e32 v45, v68, v68
	v_add_f32_e32 v47, v44, v45
	v_cvt_pk_bf16_f32 v88, v66, v67
	v_cvt_pk_bf16_f32 v89, v68, v69
	global_store_dwordx2 v[82:83], v[88:89], off offset:2048
	v_mul_f32_e32 v44, v71, v71
	v_mul_f32_e32 v45, v73, v73
	v_fmac_f32_e32 v44, v70, v70
	v_fmac_f32_e32 v45, v72, v72
	v_add_f32_e32 v44, v44, v45
	v_add_f32_e32 v47, v47, v44
	v_cvt_pk_bf16_f32 v90, v70, v71
	v_cvt_pk_bf16_f32 v91, v72, v73
	global_store_dwordx2 v[82:83], v[90:91], off offset:2560
	v_mul_f32_e32 v44, v75, v75
	v_mul_f32_e32 v45, v77, v77
	v_fmac_f32_e32 v44, v74, v74
	v_fmac_f32_e32 v45, v76, v76
	v_add_f32_e32 v44, v44, v45
	v_add_f32_e32 v47, v47, v44
	v_cvt_pk_bf16_f32 v88, v74, v75
	v_cvt_pk_bf16_f32 v89, v76, v77
	global_store_dwordx2 v[82:83], v[88:89], off offset:3072
	v_mul_f32_e32 v44, v79, v79
	v_mul_f32_e32 v45, v81, v81
	v_fmac_f32_e32 v44, v78, v78
	v_fmac_f32_e32 v45, v80, v80
	v_add_f32_e32 v44, v44, v45
	v_add_f32_e32 v47, v47, v44
	v_cvt_pk_bf16_f32 v90, v78, v79
	v_cvt_pk_bf16_f32 v91, v80, v81
	global_store_dwordx2 v[82:83], v[90:91], off offset:3584
	ds_bpermute_b32 v86, v26, v46
	ds_bpermute_b32 v87, v26, v47
	s_waitcnt lgkmcnt(0)
	v_add_f32_e32 v46, v46, v86
	v_add_f32_e32 v47, v47, v87
	ds_bpermute_b32 v86, v27, v46
	ds_bpermute_b32 v87, v27, v47
	s_waitcnt lgkmcnt(0)
	v_add_f32_e32 v46, v46, v86
	v_add_f32_e32 v47, v47, v87
	ds_bpermute_b32 v86, v28, v46
	ds_bpermute_b32 v87, v28, v47
	s_waitcnt lgkmcnt(0)
	v_add_f32_e32 v46, v46, v86
	v_add_f32_e32 v47, v47, v87
	ds_bpermute_b32 v86, v29, v46
	ds_bpermute_b32 v87, v29, v47
	s_waitcnt lgkmcnt(0)
	v_add_f32_e32 v46, v46, v86
	v_add_f32_e32 v47, v47, v87
	ds_bpermute_b32 v86, v30, v46
	ds_bpermute_b32 v87, v30, v47
	s_waitcnt lgkmcnt(0)
	v_add_f32_e32 v46, v46, v86
	v_add_f32_e32 v47, v47, v87
	ds_bpermute_b32 v86, v31, v46
	ds_bpermute_b32 v87, v31, v47
	s_waitcnt lgkmcnt(0)
	v_add_f32_e32 v46, v46, v86
	v_add_f32_e32 v47, v47, v87
	s_and_saveexec_b64 s[2:3], s[36:37]
	v_cndmask_b32_e64 v86, 0, v46, s[38:39]
	v_cndmask_b32_e64 v87, 0, v47, s[38:39]
	global_store_dword v[84:85], v86, off
	global_store_dword v[84:85], v87, off offset:64
	s_or_b64 exec, exec, s[2:3]
	s_mov_b64 vcc, 0x6000000
	v_lshl_add_u64 v[82:83], s[6:7], 0, v[18:19]
	v_lshl_add_u64 v[82:83], v[82:83], 0, vcc
	s_mov_b64 vcc, 0x1e000000
	v_lshl_add_u64 v[84:85], s[6:7], 0, v[16:17]
	v_lshl_add_u64 v[84:85], v[84:85], 0, vcc
	v_lshl_add_u64 v[20:21], v[20:21], 0, s[12:13]
	global_load_dwordx4 v[50:53], v[20:21], off offset:-4096 nt
	global_load_dwordx4 v[54:57], v[20:21], off offset:-3072 nt
	global_load_dwordx4 v[58:61], v[20:21], off offset:-2048 nt
	global_load_dwordx4 v[62:65], v[20:21], off offset:-1024 nt
	global_load_dwordx4 v[66:69], v[20:21], off nt
	global_load_dwordx4 v[70:73], v[20:21], off offset:1024 nt
	global_load_dwordx4 v[74:77], v[20:21], off offset:2048 nt
	global_load_dwordx4 v[78:81], v[20:21], off offset:3072 nt
	v_lshl_add_u64 v[16:17], v[16:17], 0, s[8:9]
	v_lshl_add_u64 v[18:19], v[18:19], 0, s[10:11]
	s_waitcnt vmcnt(16)
	v_mul_f32_e32 v44, v23, v23
	v_mul_f32_e32 v45, v25, v25
	v_fmac_f32_e32 v44, v22, v22
	v_fmac_f32_e32 v45, v24, v24
	v_add_f32_e32 v46, v44, v45
	v_cvt_pk_bf16_f32 v88, v22, v23
	v_cvt_pk_bf16_f32 v89, v24, v25
	global_store_dwordx2 v[82:83], v[88:89], off
	v_mul_f32_e32 v44, v33, v33
	v_mul_f32_e32 v45, v35, v35
	v_fmac_f32_e32 v44, v32, v32
	v_fmac_f32_e32 v45, v34, v34
	v_add_f32_e32 v44, v44, v45
	v_add_f32_e32 v46, v46, v44
	v_cvt_pk_bf16_f32 v90, v32, v33
	v_cvt_pk_bf16_f32 v91, v34, v35
	global_store_dwordx2 v[82:83], v[90:91], off offset:512
	v_mul_f32_e32 v44, v37, v37
	v_mul_f32_e32 v45, v39, v39
	v_fmac_f32_e32 v44, v36, v36
	v_fmac_f32_e32 v45, v38, v38
	v_add_f32_e32 v44, v44, v45
	v_add_f32_e32 v46, v46, v44
	v_cvt_pk_bf16_f32 v88, v36, v37
	v_cvt_pk_bf16_f32 v89, v38, v39
	global_store_dwordx2 v[82:83], v[88:89], off offset:1024
	v_mul_f32_e32 v44, v41, v41
	v_mul_f32_e32 v45, v43, v43
	v_fmac_f32_e32 v44, v40, v40
	v_fmac_f32_e32 v45, v42, v42
	v_add_f32_e32 v44, v44, v45
	v_add_f32_e32 v46, v46, v44
	v_cvt_pk_bf16_f32 v90, v40, v41
	v_cvt_pk_bf16_f32 v91, v42, v43
	global_store_dwordx2 v[82:83], v[90:91], off offset:1536
	v_mul_f32_e32 v44, v13, v13
	v_mul_f32_e32 v45, v15, v15
	v_fmac_f32_e32 v44, v12, v12
	v_fmac_f32_e32 v45, v14, v14
	v_add_f32_e32 v47, v44, v45
	v_cvt_pk_bf16_f32 v88, v12, v13
	v_cvt_pk_bf16_f32 v89, v14, v15
	global_store_dwordx2 v[82:83], v[88:89], off offset:2048
	v_mul_f32_e32 v44, v9, v9
	v_mul_f32_e32 v45, v11, v11
	v_fmac_f32_e32 v44, v8, v8
	v_fmac_f32_e32 v45, v10, v10
	v_add_f32_e32 v44, v44, v45
	v_add_f32_e32 v47, v47, v44
	v_cvt_pk_bf16_f32 v90, v8, v9
	v_cvt_pk_bf16_f32 v91, v10, v11
	global_store_dwordx2 v[82:83], v[90:91], off offset:2560
	v_mul_f32_e32 v44, v5, v5
	v_mul_f32_e32 v45, v7, v7
	v_fmac_f32_e32 v44, v4, v4
	v_fmac_f32_e32 v45, v6, v6
	v_add_f32_e32 v44, v44, v45
	v_add_f32_e32 v47, v47, v44
	v_cvt_pk_bf16_f32 v88, v4, v5
	v_cvt_pk_bf16_f32 v89, v6, v7
	global_store_dwordx2 v[82:83], v[88:89], off offset:3072
	v_mul_f32_e32 v44, v1, v1
	v_mul_f32_e32 v45, v3, v3
	v_fmac_f32_e32 v44, v0, v0
	v_fmac_f32_e32 v45, v2, v2
	v_add_f32_e32 v44, v44, v45
	v_add_f32_e32 v47, v47, v44
	v_cvt_pk_bf16_f32 v90, v0, v1
	v_cvt_pk_bf16_f32 v91, v2, v3
	global_store_dwordx2 v[82:83], v[90:91], off offset:3584
	ds_bpermute_b32 v86, v26, v46
	ds_bpermute_b32 v87, v26, v47
	s_waitcnt lgkmcnt(0)
	v_add_f32_e32 v46, v46, v86
	v_add_f32_e32 v47, v47, v87
	ds_bpermute_b32 v86, v27, v46
	ds_bpermute_b32 v87, v27, v47
	s_waitcnt lgkmcnt(0)
	v_add_f32_e32 v46, v46, v86
	v_add_f32_e32 v47, v47, v87
	ds_bpermute_b32 v86, v28, v46
	ds_bpermute_b32 v87, v28, v47
	s_waitcnt lgkmcnt(0)
	v_add_f32_e32 v46, v46, v86
	v_add_f32_e32 v47, v47, v87
	ds_bpermute_b32 v86, v29, v46
	ds_bpermute_b32 v87, v29, v47
	s_waitcnt lgkmcnt(0)
	v_add_f32_e32 v46, v46, v86
	v_add_f32_e32 v47, v47, v87
	ds_bpermute_b32 v86, v30, v46
	ds_bpermute_b32 v87, v30, v47
	s_waitcnt lgkmcnt(0)
	v_add_f32_e32 v46, v46, v86
	v_add_f32_e32 v47, v47, v87
	ds_bpermute_b32 v86, v31, v46
	ds_bpermute_b32 v87, v31, v47
	s_waitcnt lgkmcnt(0)
	v_add_f32_e32 v46, v46, v86
	v_add_f32_e32 v47, v47, v87
	s_and_saveexec_b64 s[2:3], s[36:37]
	v_cndmask_b32_e64 v86, 0, v46, s[38:39]
	v_cndmask_b32_e64 v87, 0, v47, s[38:39]
	global_store_dword v[84:85], v86, off
	global_store_dword v[84:85], v87, off offset:64
	s_or_b64 exec, exec, s[2:3]
	s_mov_b64 vcc, 0x6000000
	v_lshl_add_u64 v[82:83], s[6:7], 0, v[18:19]
	v_lshl_add_u64 v[82:83], v[82:83], 0, vcc
	s_mov_b64 vcc, 0x1e000000
	v_lshl_add_u64 v[84:85], s[6:7], 0, v[16:17]
	v_lshl_add_u64 v[84:85], v[84:85], 0, vcc
	v_lshl_add_u64 v[20:21], v[20:21], 0, s[12:13]
	global_load_dwordx4 v[22:25], v[20:21], off offset:-4096 nt
	global_load_dwordx4 v[32:35], v[20:21], off offset:-3072 nt
	global_load_dwordx4 v[36:39], v[20:21], off offset:-2048 nt
	global_load_dwordx4 v[40:43], v[20:21], off offset:-1024 nt
	global_load_dwordx4 v[12:15], v[20:21], off nt
	global_load_dwordx4 v[8:11], v[20:21], off offset:1024 nt
	global_load_dwordx4 v[4:7], v[20:21], off offset:2048 nt
	global_load_dwordx4 v[0:3], v[20:21], off offset:3072 nt
	v_lshl_add_u64 v[16:17], v[16:17], 0, s[8:9]
	v_lshl_add_u64 v[18:19], v[18:19], 0, s[10:11]
	s_waitcnt vmcnt(16)
	v_mul_f32_e32 v44, v51, v51
	v_mul_f32_e32 v45, v53, v53
	v_fmac_f32_e32 v44, v50, v50
	v_fmac_f32_e32 v45, v52, v52
	v_add_f32_e32 v46, v44, v45
	v_cvt_pk_bf16_f32 v88, v50, v51
	v_cvt_pk_bf16_f32 v89, v52, v53
	global_store_dwordx2 v[82:83], v[88:89], off
	v_mul_f32_e32 v44, v55, v55
	v_mul_f32_e32 v45, v57, v57
	v_fmac_f32_e32 v44, v54, v54
	v_fmac_f32_e32 v45, v56, v56
	v_add_f32_e32 v44, v44, v45
	v_add_f32_e32 v46, v46, v44
	v_cvt_pk_bf16_f32 v90, v54, v55
	v_cvt_pk_bf16_f32 v91, v56, v57
	global_store_dwordx2 v[82:83], v[90:91], off offset:512
	v_mul_f32_e32 v44, v59, v59
	v_mul_f32_e32 v45, v61, v61
	v_fmac_f32_e32 v44, v58, v58
	v_fmac_f32_e32 v45, v60, v60
	v_add_f32_e32 v44, v44, v45
	v_add_f32_e32 v46, v46, v44
	v_cvt_pk_bf16_f32 v88, v58, v59
	v_cvt_pk_bf16_f32 v89, v60, v61
	global_store_dwordx2 v[82:83], v[88:89], off offset:1024
	v_mul_f32_e32 v44, v63, v63
	v_mul_f32_e32 v45, v65, v65
	v_fmac_f32_e32 v44, v62, v62
	v_fmac_f32_e32 v45, v64, v64
	v_add_f32_e32 v44, v44, v45
	v_add_f32_e32 v46, v46, v44
	v_cvt_pk_bf16_f32 v90, v62, v63
	v_cvt_pk_bf16_f32 v91, v64, v65
	global_store_dwordx2 v[82:83], v[90:91], off offset:1536
	v_mul_f32_e32 v44, v67, v67
	v_mul_f32_e32 v45, v69, v69
	v_fmac_f32_e32 v44, v66, v66
	v_fmac_f32_e32 v45, v68, v68
	v_add_f32_e32 v47, v44, v45
	v_cvt_pk_bf16_f32 v88, v66, v67
	v_cvt_pk_bf16_f32 v89, v68, v69
	global_store_dwordx2 v[82:83], v[88:89], off offset:2048
	v_mul_f32_e32 v44, v71, v71
	v_mul_f32_e32 v45, v73, v73
	v_fmac_f32_e32 v44, v70, v70
	v_fmac_f32_e32 v45, v72, v72
	v_add_f32_e32 v44, v44, v45
	v_add_f32_e32 v47, v47, v44
	v_cvt_pk_bf16_f32 v90, v70, v71
	v_cvt_pk_bf16_f32 v91, v72, v73
	global_store_dwordx2 v[82:83], v[90:91], off offset:2560
	v_mul_f32_e32 v44, v75, v75
	v_mul_f32_e32 v45, v77, v77
	v_fmac_f32_e32 v44, v74, v74
	v_fmac_f32_e32 v45, v76, v76
	v_add_f32_e32 v44, v44, v45
	v_add_f32_e32 v47, v47, v44
	v_cvt_pk_bf16_f32 v88, v74, v75
	v_cvt_pk_bf16_f32 v89, v76, v77
	global_store_dwordx2 v[82:83], v[88:89], off offset:3072
	v_mul_f32_e32 v44, v79, v79
	v_mul_f32_e32 v45, v81, v81
	v_fmac_f32_e32 v44, v78, v78
	v_fmac_f32_e32 v45, v80, v80
	v_add_f32_e32 v44, v44, v45
	v_add_f32_e32 v47, v47, v44
	v_cvt_pk_bf16_f32 v90, v78, v79
	v_cvt_pk_bf16_f32 v91, v80, v81
	global_store_dwordx2 v[82:83], v[90:91], off offset:3584
	ds_bpermute_b32 v86, v26, v46
	ds_bpermute_b32 v87, v26, v47
	s_waitcnt lgkmcnt(0)
	v_add_f32_e32 v46, v46, v86
	v_add_f32_e32 v47, v47, v87
	ds_bpermute_b32 v86, v27, v46
	ds_bpermute_b32 v87, v27, v47
	s_waitcnt lgkmcnt(0)
	v_add_f32_e32 v46, v46, v86
	v_add_f32_e32 v47, v47, v87
	ds_bpermute_b32 v86, v28, v46
	ds_bpermute_b32 v87, v28, v47
	s_waitcnt lgkmcnt(0)
	v_add_f32_e32 v46, v46, v86
	v_add_f32_e32 v47, v47, v87
	ds_bpermute_b32 v86, v29, v46
	ds_bpermute_b32 v87, v29, v47
	s_waitcnt lgkmcnt(0)
	v_add_f32_e32 v46, v46, v86
	v_add_f32_e32 v47, v47, v87
	ds_bpermute_b32 v86, v30, v46
	ds_bpermute_b32 v87, v30, v47
	s_waitcnt lgkmcnt(0)
	v_add_f32_e32 v46, v46, v86
	v_add_f32_e32 v47, v47, v87
	ds_bpermute_b32 v86, v31, v46
	ds_bpermute_b32 v87, v31, v47
	s_waitcnt lgkmcnt(0)
	v_add_f32_e32 v46, v46, v86
	v_add_f32_e32 v47, v47, v87
	s_and_saveexec_b64 s[2:3], s[36:37]
	v_cndmask_b32_e64 v86, 0, v46, s[38:39]
	v_cndmask_b32_e64 v87, 0, v47, s[38:39]
	global_store_dword v[84:85], v86, off
	global_store_dword v[84:85], v87, off offset:64
	s_or_b64 exec, exec, s[2:3]
	s_mov_b64 vcc, 0x6000000
	v_lshl_add_u64 v[82:83], s[6:7], 0, v[18:19]
	v_lshl_add_u64 v[82:83], v[82:83], 0, vcc
	s_mov_b64 vcc, 0x1e000000
	v_lshl_add_u64 v[84:85], s[6:7], 0, v[16:17]
	v_lshl_add_u64 v[84:85], v[84:85], 0, vcc
	v_lshl_add_u64 v[20:21], v[20:21], 0, s[12:13]
	global_load_dwordx4 v[50:53], v[20:21], off offset:-4096 nt
	global_load_dwordx4 v[54:57], v[20:21], off offset:-3072 nt
	global_load_dwordx4 v[58:61], v[20:21], off offset:-2048 nt
	global_load_dwordx4 v[62:65], v[20:21], off offset:-1024 nt
	global_load_dwordx4 v[66:69], v[20:21], off nt
	global_load_dwordx4 v[70:73], v[20:21], off offset:1024 nt
	global_load_dwordx4 v[74:77], v[20:21], off offset:2048 nt
	global_load_dwordx4 v[78:81], v[20:21], off offset:3072 nt
	v_lshl_add_u64 v[16:17], v[16:17], 0, s[8:9]
	v_lshl_add_u64 v[18:19], v[18:19], 0, s[10:11]
	s_waitcnt vmcnt(16)
	v_mul_f32_e32 v44, v23, v23
	v_mul_f32_e32 v45, v25, v25
	v_fmac_f32_e32 v44, v22, v22
	v_fmac_f32_e32 v45, v24, v24
	v_add_f32_e32 v46, v44, v45
	v_cvt_pk_bf16_f32 v88, v22, v23
	v_cvt_pk_bf16_f32 v89, v24, v25
	global_store_dwordx2 v[82:83], v[88:89], off
	v_mul_f32_e32 v44, v33, v33
	v_mul_f32_e32 v45, v35, v35
	v_fmac_f32_e32 v44, v32, v32
	v_fmac_f32_e32 v45, v34, v34
	v_add_f32_e32 v44, v44, v45
	v_add_f32_e32 v46, v46, v44
	v_cvt_pk_bf16_f32 v90, v32, v33
	v_cvt_pk_bf16_f32 v91, v34, v35
	global_store_dwordx2 v[82:83], v[90:91], off offset:512
	v_mul_f32_e32 v44, v37, v37
	v_mul_f32_e32 v45, v39, v39
	v_fmac_f32_e32 v44, v36, v36
	v_fmac_f32_e32 v45, v38, v38
	v_add_f32_e32 v44, v44, v45
	v_add_f32_e32 v46, v46, v44
	v_cvt_pk_bf16_f32 v88, v36, v37
	v_cvt_pk_bf16_f32 v89, v38, v39
	global_store_dwordx2 v[82:83], v[88:89], off offset:1024
	v_mul_f32_e32 v44, v41, v41
	v_mul_f32_e32 v45, v43, v43
	v_fmac_f32_e32 v44, v40, v40
	v_fmac_f32_e32 v45, v42, v42
	v_add_f32_e32 v44, v44, v45
	v_add_f32_e32 v46, v46, v44
	v_cvt_pk_bf16_f32 v90, v40, v41
	v_cvt_pk_bf16_f32 v91, v42, v43
	global_store_dwordx2 v[82:83], v[90:91], off offset:1536
	v_mul_f32_e32 v44, v13, v13
	v_mul_f32_e32 v45, v15, v15
	v_fmac_f32_e32 v44, v12, v12
	v_fmac_f32_e32 v45, v14, v14
	v_add_f32_e32 v47, v44, v45
	v_cvt_pk_bf16_f32 v88, v12, v13
	v_cvt_pk_bf16_f32 v89, v14, v15
	global_store_dwordx2 v[82:83], v[88:89], off offset:2048
	v_mul_f32_e32 v44, v9, v9
	v_mul_f32_e32 v45, v11, v11
	v_fmac_f32_e32 v44, v8, v8
	v_fmac_f32_e32 v45, v10, v10
	v_add_f32_e32 v44, v44, v45
	v_add_f32_e32 v47, v47, v44
	v_cvt_pk_bf16_f32 v90, v8, v9
	v_cvt_pk_bf16_f32 v91, v10, v11
	global_store_dwordx2 v[82:83], v[90:91], off offset:2560
	v_mul_f32_e32 v44, v5, v5
	v_mul_f32_e32 v45, v7, v7
	v_fmac_f32_e32 v44, v4, v4
	v_fmac_f32_e32 v45, v6, v6
	v_add_f32_e32 v44, v44, v45
	v_add_f32_e32 v47, v47, v44
	v_cvt_pk_bf16_f32 v88, v4, v5
	v_cvt_pk_bf16_f32 v89, v6, v7
	global_store_dwordx2 v[82:83], v[88:89], off offset:3072
	v_mul_f32_e32 v44, v1, v1
	v_mul_f32_e32 v45, v3, v3
	v_fmac_f32_e32 v44, v0, v0
	v_fmac_f32_e32 v45, v2, v2
	v_add_f32_e32 v44, v44, v45
	v_add_f32_e32 v47, v47, v44
	v_cvt_pk_bf16_f32 v90, v0, v1
	v_cvt_pk_bf16_f32 v91, v2, v3
	global_store_dwordx2 v[82:83], v[90:91], off offset:3584
	ds_bpermute_b32 v86, v26, v46
	ds_bpermute_b32 v87, v26, v47
	s_waitcnt lgkmcnt(0)
	v_add_f32_e32 v46, v46, v86
	v_add_f32_e32 v47, v47, v87
	ds_bpermute_b32 v86, v27, v46
	ds_bpermute_b32 v87, v27, v47
	s_waitcnt lgkmcnt(0)
	v_add_f32_e32 v46, v46, v86
	v_add_f32_e32 v47, v47, v87
	ds_bpermute_b32 v86, v28, v46
	ds_bpermute_b32 v87, v28, v47
	s_waitcnt lgkmcnt(0)
	v_add_f32_e32 v46, v46, v86
	v_add_f32_e32 v47, v47, v87
	ds_bpermute_b32 v86, v29, v46
	ds_bpermute_b32 v87, v29, v47
	s_waitcnt lgkmcnt(0)
	v_add_f32_e32 v46, v46, v86
	v_add_f32_e32 v47, v47, v87
	ds_bpermute_b32 v86, v30, v46
	ds_bpermute_b32 v87, v30, v47
	s_waitcnt lgkmcnt(0)
	v_add_f32_e32 v46, v46, v86
	v_add_f32_e32 v47, v47, v87
	ds_bpermute_b32 v86, v31, v46
	ds_bpermute_b32 v87, v31, v47
	s_waitcnt lgkmcnt(0)
	v_add_f32_e32 v46, v46, v86
	v_add_f32_e32 v47, v47, v87
	s_and_saveexec_b64 s[2:3], s[36:37]
	v_cndmask_b32_e64 v86, 0, v46, s[38:39]
	v_cndmask_b32_e64 v87, 0, v47, s[38:39]
	global_store_dword v[84:85], v86, off
	global_store_dword v[84:85], v87, off offset:64
	s_or_b64 exec, exec, s[2:3]
	s_mov_b64 vcc, 0x6000000
	v_lshl_add_u64 v[82:83], s[6:7], 0, v[18:19]
	v_lshl_add_u64 v[82:83], v[82:83], 0, vcc
	s_mov_b64 vcc, 0x1e000000
	v_lshl_add_u64 v[84:85], s[6:7], 0, v[16:17]
	v_lshl_add_u64 v[84:85], v[84:85], 0, vcc
	v_lshl_add_u64 v[16:17], v[16:17], 0, s[8:9]
	v_lshl_add_u64 v[18:19], v[18:19], 0, s[10:11]
	s_waitcnt vmcnt(8)
	v_mul_f32_e32 v44, v51, v51
	v_mul_f32_e32 v45, v53, v53
	v_fmac_f32_e32 v44, v50, v50
	v_fmac_f32_e32 v45, v52, v52
	v_add_f32_e32 v46, v44, v45
	v_cvt_pk_bf16_f32 v88, v50, v51
	v_cvt_pk_bf16_f32 v89, v52, v53
	global_store_dwordx2 v[82:83], v[88:89], off
	v_mul_f32_e32 v44, v55, v55
	v_mul_f32_e32 v45, v57, v57
	v_fmac_f32_e32 v44, v54, v54
	v_fmac_f32_e32 v45, v56, v56
	v_add_f32_e32 v44, v44, v45
	v_add_f32_e32 v46, v46, v44
	v_cvt_pk_bf16_f32 v90, v54, v55
	v_cvt_pk_bf16_f32 v91, v56, v57
	global_store_dwordx2 v[82:83], v[90:91], off offset:512
	v_mul_f32_e32 v44, v59, v59
	v_mul_f32_e32 v45, v61, v61
	v_fmac_f32_e32 v44, v58, v58
	v_fmac_f32_e32 v45, v60, v60
	v_add_f32_e32 v44, v44, v45
	v_add_f32_e32 v46, v46, v44
	v_cvt_pk_bf16_f32 v88, v58, v59
	v_cvt_pk_bf16_f32 v89, v60, v61
	global_store_dwordx2 v[82:83], v[88:89], off offset:1024
	v_mul_f32_e32 v44, v63, v63
	v_mul_f32_e32 v45, v65, v65
	v_fmac_f32_e32 v44, v62, v62
	v_fmac_f32_e32 v45, v64, v64
	v_add_f32_e32 v44, v44, v45
	v_add_f32_e32 v46, v46, v44
	v_cvt_pk_bf16_f32 v90, v62, v63
	v_cvt_pk_bf16_f32 v91, v64, v65
	global_store_dwordx2 v[82:83], v[90:91], off offset:1536
	v_mul_f32_e32 v44, v67, v67
	v_mul_f32_e32 v45, v69, v69
	v_fmac_f32_e32 v44, v66, v66
	v_fmac_f32_e32 v45, v68, v68
	v_add_f32_e32 v47, v44, v45
	v_cvt_pk_bf16_f32 v88, v66, v67
	v_cvt_pk_bf16_f32 v89, v68, v69
	global_store_dwordx2 v[82:83], v[88:89], off offset:2048
	v_mul_f32_e32 v44, v71, v71
	v_mul_f32_e32 v45, v73, v73
	v_fmac_f32_e32 v44, v70, v70
	v_fmac_f32_e32 v45, v72, v72
	v_add_f32_e32 v44, v44, v45
	v_add_f32_e32 v47, v47, v44
	v_cvt_pk_bf16_f32 v90, v70, v71
	v_cvt_pk_bf16_f32 v91, v72, v73
	global_store_dwordx2 v[82:83], v[90:91], off offset:2560
	v_mul_f32_e32 v44, v75, v75
	v_mul_f32_e32 v45, v77, v77
	v_fmac_f32_e32 v44, v74, v74
	v_fmac_f32_e32 v45, v76, v76
	v_add_f32_e32 v44, v44, v45
	v_add_f32_e32 v47, v47, v44
	v_cvt_pk_bf16_f32 v88, v74, v75
	v_cvt_pk_bf16_f32 v89, v76, v77
	global_store_dwordx2 v[82:83], v[88:89], off offset:3072
	v_mul_f32_e32 v44, v79, v79
	v_mul_f32_e32 v45, v81, v81
	v_fmac_f32_e32 v44, v78, v78
	v_fmac_f32_e32 v45, v80, v80
	v_add_f32_e32 v44, v44, v45
	v_add_f32_e32 v47, v47, v44
	v_cvt_pk_bf16_f32 v90, v78, v79
	v_cvt_pk_bf16_f32 v91, v80, v81
	global_store_dwordx2 v[82:83], v[90:91], off offset:3584
	ds_bpermute_b32 v86, v26, v46
	ds_bpermute_b32 v87, v26, v47
	s_waitcnt lgkmcnt(0)
	v_add_f32_e32 v46, v46, v86
	v_add_f32_e32 v47, v47, v87
	ds_bpermute_b32 v86, v27, v46
	ds_bpermute_b32 v87, v27, v47
	s_waitcnt lgkmcnt(0)
	v_add_f32_e32 v46, v46, v86
	v_add_f32_e32 v47, v47, v87
	ds_bpermute_b32 v86, v28, v46
	ds_bpermute_b32 v87, v28, v47
	s_waitcnt lgkmcnt(0)
	v_add_f32_e32 v46, v46, v86
	v_add_f32_e32 v47, v47, v87
	ds_bpermute_b32 v86, v29, v46
	ds_bpermute_b32 v87, v29, v47
	s_waitcnt lgkmcnt(0)
	v_add_f32_e32 v46, v46, v86
	v_add_f32_e32 v47, v47, v87
	ds_bpermute_b32 v86, v30, v46
	ds_bpermute_b32 v87, v30, v47
	s_waitcnt lgkmcnt(0)
	v_add_f32_e32 v46, v46, v86
	v_add_f32_e32 v47, v47, v87
	ds_bpermute_b32 v86, v31, v46
	ds_bpermute_b32 v87, v31, v47
	s_waitcnt lgkmcnt(0)
	v_add_f32_e32 v46, v46, v86
	v_add_f32_e32 v47, v47, v87
	s_and_saveexec_b64 s[2:3], s[36:37]
	v_cndmask_b32_e64 v86, 0, v46, s[38:39]
	v_cndmask_b32_e64 v87, 0, v47, s[38:39]
	global_store_dword v[84:85], v86, off
	global_store_dword v[84:85], v87, off offset:64
	s_or_b64 exec, exec, s[2:3]
	s_branch .LBB0_374
